# G2 layer0 epilogue software-pipelined residual loads; P0 silu staging loop batched
# speedup vs baseline: 1.0113x; 1.0113x over previous
; __device__ __forceinline__ float siluf_(float x) { return x * sigmoidf_(x); }
; __device__ __forceinline__ void p0_phase(LAS unsigned char* lds, const float* c, const float* w_ada, const float* b_ada, const float* w_in, const float* w_out,
;                                          float* mod, bf16* win_t, bf16* wout_t, int tid, int wid, int lane) {
;     ...
;         for (int i = tid; i < 32 * 1024; i += 512) { const float cv = c[i]; cs[i] = siluf_(cv); }
.LBB0_19:
	global_load_dword v16, v[0:1], off
	v_lshl_add_u64 v[0:1], v[0:1], 0, s[12:13]
	global_load_dword v17, v[0:1], off
	v_lshl_add_u64 v[0:1], v[0:1], 0, s[12:13]
	global_load_dword v18, v[0:1], off
	v_lshl_add_u64 v[0:1], v[0:1], 0, s[12:13]
	global_load_dword v19, v[0:1], off
	v_lshl_add_u64 v[0:1], v[0:1], 0, s[12:13]
	global_load_dword v20, v[0:1], off
	v_lshl_add_u64 v[0:1], v[0:1], 0, s[12:13]
	global_load_dword v21, v[0:1], off
	v_lshl_add_u64 v[0:1], v[0:1], 0, s[12:13]
	global_load_dword v22, v[0:1], off
	v_lshl_add_u64 v[0:1], v[0:1], 0, s[12:13]
	global_load_dword v23, v[0:1], off
	v_lshl_add_u64 v[0:1], v[0:1], 0, s[12:13]
	global_load_dword v24, v[0:1], off
	v_lshl_add_u64 v[0:1], v[0:1], 0, s[12:13]
	global_load_dword v25, v[0:1], off
	v_lshl_add_u64 v[0:1], v[0:1], 0, s[12:13]
	global_load_dword v26, v[0:1], off
	v_lshl_add_u64 v[0:1], v[0:1], 0, s[12:13]
	global_load_dword v27, v[0:1], off
	v_lshl_add_u64 v[0:1], v[0:1], 0, s[12:13]
	global_load_dword v28, v[0:1], off
	v_lshl_add_u64 v[0:1], v[0:1], 0, s[12:13]
	global_load_dword v29, v[0:1], off
	v_lshl_add_u64 v[0:1], v[0:1], 0, s[12:13]
	global_load_dword v30, v[0:1], off
	v_lshl_add_u64 v[0:1], v[0:1], 0, s[12:13]
	global_load_dword v31, v[0:1], off
	v_lshl_add_u64 v[0:1], v[0:1], 0, s[12:13]
	s_waitcnt vmcnt(15)
	v_mul_f32_e32 v32, 0xbfb8aa3b, v16
	v_exp_f32_e32 v32, v32
	s_nop 0
	v_add_f32_e32 v32, 1.0, v32
	v_rcp_f32_e32 v32, v32
	s_nop 0
	v_mul_f32_e32 v16, v16, v32
	ds_write_b32 v2, v16
	s_waitcnt vmcnt(14)
	v_mul_f32_e32 v32, 0xbfb8aa3b, v17
	v_exp_f32_e32 v32, v32
	s_nop 0
	v_add_f32_e32 v32, 1.0, v32
	v_rcp_f32_e32 v32, v32
	s_nop 0
	v_mul_f32_e32 v17, v17, v32
	ds_write_b32 v2, v17 offset:2048
	s_waitcnt vmcnt(13)
	v_mul_f32_e32 v32, 0xbfb8aa3b, v18
	v_exp_f32_e32 v32, v32
	s_nop 0
	v_add_f32_e32 v32, 1.0, v32
	v_rcp_f32_e32 v32, v32
	s_nop 0
	v_mul_f32_e32 v18, v18, v32
	ds_write_b32 v2, v18 offset:4096
	s_waitcnt vmcnt(12)
	v_mul_f32_e32 v32, 0xbfb8aa3b, v19
	v_exp_f32_e32 v32, v32
	s_nop 0
	v_add_f32_e32 v32, 1.0, v32
	v_rcp_f32_e32 v32, v32
	s_nop 0
	v_mul_f32_e32 v19, v19, v32
	ds_write_b32 v2, v19 offset:6144
	s_waitcnt vmcnt(11)
	v_mul_f32_e32 v32, 0xbfb8aa3b, v20
	v_exp_f32_e32 v32, v32
	s_nop 0
	v_add_f32_e32 v32, 1.0, v32
	v_rcp_f32_e32 v32, v32
	s_nop 0
	v_mul_f32_e32 v20, v20, v32
	ds_write_b32 v2, v20 offset:8192
	s_waitcnt vmcnt(10)
	v_mul_f32_e32 v32, 0xbfb8aa3b, v21
	v_exp_f32_e32 v32, v32
	s_nop 0
	v_add_f32_e32 v32, 1.0, v32
	v_rcp_f32_e32 v32, v32
	s_nop 0
	v_mul_f32_e32 v21, v21, v32
	ds_write_b32 v2, v21 offset:10240
	s_waitcnt vmcnt(9)
	v_mul_f32_e32 v32, 0xbfb8aa3b, v22
	v_exp_f32_e32 v32, v32
	s_nop 0
	v_add_f32_e32 v32, 1.0, v32
	v_rcp_f32_e32 v32, v32
	s_nop 0
	v_mul_f32_e32 v22, v22, v32
	ds_write_b32 v2, v22 offset:12288
	s_waitcnt vmcnt(8)
	v_mul_f32_e32 v32, 0xbfb8aa3b, v23
	v_exp_f32_e32 v32, v32
	s_nop 0
	v_add_f32_e32 v32, 1.0, v32
	v_rcp_f32_e32 v32, v32
	s_nop 0
	v_mul_f32_e32 v23, v23, v32
	ds_write_b32 v2, v23 offset:14336
	s_waitcnt vmcnt(7)
	v_mul_f32_e32 v32, 0xbfb8aa3b, v24
	v_exp_f32_e32 v32, v32
	s_nop 0
	v_add_f32_e32 v32, 1.0, v32
	v_rcp_f32_e32 v32, v32
	s_nop 0
	v_mul_f32_e32 v24, v24, v32
	ds_write_b32 v2, v24 offset:16384
	s_waitcnt vmcnt(6)
	v_mul_f32_e32 v32, 0xbfb8aa3b, v25
	v_exp_f32_e32 v32, v32
	s_nop 0
	v_add_f32_e32 v32, 1.0, v32
	v_rcp_f32_e32 v32, v32
	s_nop 0
	v_mul_f32_e32 v25, v25, v32
	ds_write_b32 v2, v25 offset:18432
	s_waitcnt vmcnt(5)
	v_mul_f32_e32 v32, 0xbfb8aa3b, v26
	v_exp_f32_e32 v32, v32
	s_nop 0
	v_add_f32_e32 v32, 1.0, v32
	v_rcp_f32_e32 v32, v32
	s_nop 0
	v_mul_f32_e32 v26, v26, v32
	ds_write_b32 v2, v26 offset:20480
	s_waitcnt vmcnt(4)
	v_mul_f32_e32 v32, 0xbfb8aa3b, v27
	v_exp_f32_e32 v32, v32
	s_nop 0
	v_add_f32_e32 v32, 1.0, v32
	v_rcp_f32_e32 v32, v32
	s_nop 0
	v_mul_f32_e32 v27, v27, v32
	ds_write_b32 v2, v27 offset:22528
	s_waitcnt vmcnt(3)
	v_mul_f32_e32 v32, 0xbfb8aa3b, v28
	v_exp_f32_e32 v32, v32
	s_nop 0
	v_add_f32_e32 v32, 1.0, v32
	v_rcp_f32_e32 v32, v32
	s_nop 0
	v_mul_f32_e32 v28, v28, v32
	ds_write_b32 v2, v28 offset:24576
	s_waitcnt vmcnt(2)
	v_mul_f32_e32 v32, 0xbfb8aa3b, v29
	v_exp_f32_e32 v32, v32
	s_nop 0
	v_add_f32_e32 v32, 1.0, v32
	v_rcp_f32_e32 v32, v32
	s_nop 0
	v_mul_f32_e32 v29, v29, v32
	ds_write_b32 v2, v29 offset:26624
	s_waitcnt vmcnt(1)
	v_mul_f32_e32 v32, 0xbfb8aa3b, v30
	v_exp_f32_e32 v32, v32
	s_nop 0
	v_add_f32_e32 v32, 1.0, v32
	v_rcp_f32_e32 v32, v32
	s_nop 0
	v_mul_f32_e32 v30, v30, v32
	ds_write_b32 v2, v30 offset:28672
	s_waitcnt vmcnt(0)
	v_mul_f32_e32 v32, 0xbfb8aa3b, v31
	v_exp_f32_e32 v32, v32
	s_nop 0
	v_add_f32_e32 v32, 1.0, v32
	v_rcp_f32_e32 v32, v32
	s_nop 0
	v_mul_f32_e32 v31, v31, v32
	ds_write_b32 v2, v31 offset:30720
	v_add_u32_e32 v2, 0x8000, v2
	global_load_dword v16, v[0:1], off
	v_lshl_add_u64 v[0:1], v[0:1], 0, s[12:13]
	global_load_dword v17, v[0:1], off
	v_lshl_add_u64 v[0:1], v[0:1], 0, s[12:13]
	global_load_dword v18, v[0:1], off
	v_lshl_add_u64 v[0:1], v[0:1], 0, s[12:13]
	global_load_dword v19, v[0:1], off
	v_lshl_add_u64 v[0:1], v[0:1], 0, s[12:13]
	global_load_dword v20, v[0:1], off
	v_lshl_add_u64 v[0:1], v[0:1], 0, s[12:13]
	global_load_dword v21, v[0:1], off
	v_lshl_add_u64 v[0:1], v[0:1], 0, s[12:13]
	global_load_dword v22, v[0:1], off
	v_lshl_add_u64 v[0:1], v[0:1], 0, s[12:13]
	global_load_dword v23, v[0:1], off
	v_lshl_add_u64 v[0:1], v[0:1], 0, s[12:13]
	global_load_dword v24, v[0:1], off
	v_lshl_add_u64 v[0:1], v[0:1], 0, s[12:13]
	global_load_dword v25, v[0:1], off
	v_lshl_add_u64 v[0:1], v[0:1], 0, s[12:13]
	global_load_dword v26, v[0:1], off
	v_lshl_add_u64 v[0:1], v[0:1], 0, s[12:13]
	global_load_dword v27, v[0:1], off
	v_lshl_add_u64 v[0:1], v[0:1], 0, s[12:13]
	global_load_dword v28, v[0:1], off
	v_lshl_add_u64 v[0:1], v[0:1], 0, s[12:13]
	global_load_dword v29, v[0:1], off
	v_lshl_add_u64 v[0:1], v[0:1], 0, s[12:13]
	global_load_dword v30, v[0:1], off
	v_lshl_add_u64 v[0:1], v[0:1], 0, s[12:13]
	global_load_dword v31, v[0:1], off
	v_lshl_add_u64 v[0:1], v[0:1], 0, s[12:13]
	s_waitcnt vmcnt(15)
; __device__ __forceinline__ float siluf_(float x) { return x * sigmoidf_(x); }
; __device__ __forceinline__ void p0_phase(LAS unsigned char* lds, const float* c, const float* w_ada, const float* b_ada, const float* w_in, const float* w_out,
;                                          float* mod, bf16* win_t, bf16* wout_t, int tid, int wid, int lane) {
;     ...
;         for (int i = tid; i < 32 * 1024; i += 512) { const float cv = c[i]; cs[i] = siluf_(cv); }
	v_mul_f32_e32 v32, 0xbfb8aa3b, v16
	v_exp_f32_e32 v32, v32
	s_nop 0
	v_add_f32_e32 v32, 1.0, v32
	v_rcp_f32_e32 v32, v32
	s_nop 0
	v_mul_f32_e32 v16, v16, v32
	ds_write_b32 v2, v16
	s_waitcnt vmcnt(14)
	v_mul_f32_e32 v32, 0xbfb8aa3b, v17
	v_exp_f32_e32 v32, v32
	s_nop 0
	v_add_f32_e32 v32, 1.0, v32
	v_rcp_f32_e32 v32, v32
	s_nop 0
	v_mul_f32_e32 v17, v17, v32
	ds_write_b32 v2, v17 offset:2048
	s_waitcnt vmcnt(13)
	v_mul_f32_e32 v32, 0xbfb8aa3b, v18
	v_exp_f32_e32 v32, v32
	s_nop 0
	v_add_f32_e32 v32, 1.0, v32
	v_rcp_f32_e32 v32, v32
	s_nop 0
	v_mul_f32_e32 v18, v18, v32
	ds_write_b32 v2, v18 offset:4096
	s_waitcnt vmcnt(12)
	v_mul_f32_e32 v32, 0xbfb8aa3b, v19
	v_exp_f32_e32 v32, v32
	s_nop 0
	v_add_f32_e32 v32, 1.0, v32
	v_rcp_f32_e32 v32, v32
	s_nop 0
	v_mul_f32_e32 v19, v19, v32
	ds_write_b32 v2, v19 offset:6144
	s_waitcnt vmcnt(11)
	v_mul_f32_e32 v32, 0xbfb8aa3b, v20
	v_exp_f32_e32 v32, v32
	s_nop 0
	v_add_f32_e32 v32, 1.0, v32
	v_rcp_f32_e32 v32, v32
	s_nop 0
	v_mul_f32_e32 v20, v20, v32
	ds_write_b32 v2, v20 offset:8192
	s_waitcnt vmcnt(10)
	v_mul_f32_e32 v32, 0xbfb8aa3b, v21
	v_exp_f32_e32 v32, v32
	s_nop 0
	v_add_f32_e32 v32, 1.0, v32
	v_rcp_f32_e32 v32, v32
	s_nop 0
	v_mul_f32_e32 v21, v21, v32
	ds_write_b32 v2, v21 offset:10240
	s_waitcnt vmcnt(9)
	v_mul_f32_e32 v32, 0xbfb8aa3b, v22
	v_exp_f32_e32 v32, v32
	s_nop 0
	v_add_f32_e32 v32, 1.0, v32
	v_rcp_f32_e32 v32, v32
	s_nop 0
	v_mul_f32_e32 v22, v22, v32
	ds_write_b32 v2, v22 offset:12288
	s_waitcnt vmcnt(8)
	v_mul_f32_e32 v32, 0xbfb8aa3b, v23
	v_exp_f32_e32 v32, v32
	s_nop 0
	v_add_f32_e32 v32, 1.0, v32
	v_rcp_f32_e32 v32, v32
	s_nop 0
	v_mul_f32_e32 v23, v23, v32
	ds_write_b32 v2, v23 offset:14336
	s_waitcnt vmcnt(7)
	v_mul_f32_e32 v32, 0xbfb8aa3b, v24
	v_exp_f32_e32 v32, v32
	s_nop 0
	v_add_f32_e32 v32, 1.0, v32
	v_rcp_f32_e32 v32, v32
	s_nop 0
	v_mul_f32_e32 v24, v24, v32
	ds_write_b32 v2, v24 offset:16384
	s_waitcnt vmcnt(6)
	v_mul_f32_e32 v32, 0xbfb8aa3b, v25
	v_exp_f32_e32 v32, v32
	s_nop 0
	v_add_f32_e32 v32, 1.0, v32
	v_rcp_f32_e32 v32, v32
	s_nop 0
	v_mul_f32_e32 v25, v25, v32
	ds_write_b32 v2, v25 offset:18432
	s_waitcnt vmcnt(5)
	v_mul_f32_e32 v32, 0xbfb8aa3b, v26
	v_exp_f32_e32 v32, v32
	s_nop 0
	v_add_f32_e32 v32, 1.0, v32
	v_rcp_f32_e32 v32, v32
	s_nop 0
	v_mul_f32_e32 v26, v26, v32
	ds_write_b32 v2, v26 offset:20480
	s_waitcnt vmcnt(4)
	v_mul_f32_e32 v32, 0xbfb8aa3b, v27
	v_exp_f32_e32 v32, v32
	s_nop 0
	v_add_f32_e32 v32, 1.0, v32
	v_rcp_f32_e32 v32, v32
	s_nop 0
	v_mul_f32_e32 v27, v27, v32
	ds_write_b32 v2, v27 offset:22528
	s_waitcnt vmcnt(3)
	v_mul_f32_e32 v32, 0xbfb8aa3b, v28
	v_exp_f32_e32 v32, v32
	s_nop 0
	v_add_f32_e32 v32, 1.0, v32
	v_rcp_f32_e32 v32, v32
	s_nop 0
	v_mul_f32_e32 v28, v28, v32
	ds_write_b32 v2, v28 offset:24576
	s_waitcnt vmcnt(2)
	v_mul_f32_e32 v32, 0xbfb8aa3b, v29
	v_exp_f32_e32 v32, v32
	s_nop 0
	v_add_f32_e32 v32, 1.0, v32
	v_rcp_f32_e32 v32, v32
	s_nop 0
	v_mul_f32_e32 v29, v29, v32
	ds_write_b32 v2, v29 offset:26624
	s_waitcnt vmcnt(1)
	v_mul_f32_e32 v32, 0xbfb8aa3b, v30
	v_exp_f32_e32 v32, v32
	s_nop 0
	v_add_f32_e32 v32, 1.0, v32
	v_rcp_f32_e32 v32, v32
	s_nop 0
	v_mul_f32_e32 v30, v30, v32
	ds_write_b32 v2, v30 offset:28672
	s_waitcnt vmcnt(0)
	v_mul_f32_e32 v32, 0xbfb8aa3b, v31
	v_exp_f32_e32 v32, v32
	s_nop 0
	v_add_f32_e32 v32, 1.0, v32
	v_rcp_f32_e32 v32, v32
	s_nop 0
	v_mul_f32_e32 v31, v31, v32
	ds_write_b32 v2, v31 offset:30720
	v_add_u32_e32 v2, 0x8000, v2
	global_load_dword v16, v[0:1], off
	v_lshl_add_u64 v[0:1], v[0:1], 0, s[12:13]
	global_load_dword v17, v[0:1], off
	v_lshl_add_u64 v[0:1], v[0:1], 0, s[12:13]
	global_load_dword v18, v[0:1], off
	v_lshl_add_u64 v[0:1], v[0:1], 0, s[12:13]
	global_load_dword v19, v[0:1], off
	v_lshl_add_u64 v[0:1], v[0:1], 0, s[12:13]
	global_load_dword v20, v[0:1], off
	v_lshl_add_u64 v[0:1], v[0:1], 0, s[12:13]
	global_load_dword v21, v[0:1], off
	v_lshl_add_u64 v[0:1], v[0:1], 0, s[12:13]
	global_load_dword v22, v[0:1], off
	v_lshl_add_u64 v[0:1], v[0:1], 0, s[12:13]
	global_load_dword v23, v[0:1], off
	v_lshl_add_u64 v[0:1], v[0:1], 0, s[12:13]
	global_load_dword v24, v[0:1], off
	v_lshl_add_u64 v[0:1], v[0:1], 0, s[12:13]
	global_load_dword v25, v[0:1], off
	v_lshl_add_u64 v[0:1], v[0:1], 0, s[12:13]
	global_load_dword v26, v[0:1], off
	v_lshl_add_u64 v[0:1], v[0:1], 0, s[12:13]
	global_load_dword v27, v[0:1], off
	v_lshl_add_u64 v[0:1], v[0:1], 0, s[12:13]
	global_load_dword v28, v[0:1], off
	v_lshl_add_u64 v[0:1], v[0:1], 0, s[12:13]
	global_load_dword v29, v[0:1], off
	v_lshl_add_u64 v[0:1], v[0:1], 0, s[12:13]
	global_load_dword v30, v[0:1], off
	v_lshl_add_u64 v[0:1], v[0:1], 0, s[12:13]
	global_load_dword v31, v[0:1], off
	v_lshl_add_u64 v[0:1], v[0:1], 0, s[12:13]
	s_waitcnt vmcnt(15)
	v_mul_f32_e32 v32, 0xbfb8aa3b, v16
	v_exp_f32_e32 v32, v32
	s_nop 0
	v_add_f32_e32 v32, 1.0, v32
	v_rcp_f32_e32 v32, v32
	s_nop 0
	v_mul_f32_e32 v16, v16, v32
	ds_write_b32 v2, v16
	s_waitcnt vmcnt(14)
	v_mul_f32_e32 v32, 0xbfb8aa3b, v17
	v_exp_f32_e32 v32, v32
	s_nop 0
	v_add_f32_e32 v32, 1.0, v32
	v_rcp_f32_e32 v32, v32
	s_nop 0
	v_mul_f32_e32 v17, v17, v32
	ds_write_b32 v2, v17 offset:2048
	s_waitcnt vmcnt(13)
	v_mul_f32_e32 v32, 0xbfb8aa3b, v18
	v_exp_f32_e32 v32, v32
	s_nop 0
	v_add_f32_e32 v32, 1.0, v32
	v_rcp_f32_e32 v32, v32
	s_nop 0
	v_mul_f32_e32 v18, v18, v32
	ds_write_b32 v2, v18 offset:4096
	s_waitcnt vmcnt(12)
	v_mul_f32_e32 v32, 0xbfb8aa3b, v19
	v_exp_f32_e32 v32, v32
	s_nop 0
	v_add_f32_e32 v32, 1.0, v32
	v_rcp_f32_e32 v32, v32
	s_nop 0
	v_mul_f32_e32 v19, v19, v32
	ds_write_b32 v2, v19 offset:6144
	s_waitcnt vmcnt(11)
; __device__ __forceinline__ float siluf_(float x) { return x * sigmoidf_(x); }
; __device__ __forceinline__ void p0_phase(LAS unsigned char* lds, const float* c, const float* w_ada, const float* b_ada, const float* w_in, const float* w_out,
;                                          float* mod, bf16* win_t, bf16* wout_t, int tid, int wid, int lane) {
;     ...
;         for (int i = tid; i < 32 * 1024; i += 512) { const float cv = c[i]; cs[i] = siluf_(cv); }
	v_mul_f32_e32 v32, 0xbfb8aa3b, v20
	v_exp_f32_e32 v32, v32
	s_nop 0
	v_add_f32_e32 v32, 1.0, v32
	v_rcp_f32_e32 v32, v32
	s_nop 0
	v_mul_f32_e32 v20, v20, v32
	ds_write_b32 v2, v20 offset:8192
	s_waitcnt vmcnt(10)
	v_mul_f32_e32 v32, 0xbfb8aa3b, v21
	v_exp_f32_e32 v32, v32
	s_nop 0
	v_add_f32_e32 v32, 1.0, v32
	v_rcp_f32_e32 v32, v32
	s_nop 0
	v_mul_f32_e32 v21, v21, v32
	ds_write_b32 v2, v21 offset:10240
	s_waitcnt vmcnt(9)
	v_mul_f32_e32 v32, 0xbfb8aa3b, v22
	v_exp_f32_e32 v32, v32
	s_nop 0
	v_add_f32_e32 v32, 1.0, v32
	v_rcp_f32_e32 v32, v32
	s_nop 0
	v_mul_f32_e32 v22, v22, v32
	ds_write_b32 v2, v22 offset:12288
	s_waitcnt vmcnt(8)
	v_mul_f32_e32 v32, 0xbfb8aa3b, v23
	v_exp_f32_e32 v32, v32
	s_nop 0
	v_add_f32_e32 v32, 1.0, v32
	v_rcp_f32_e32 v32, v32
	s_nop 0
	v_mul_f32_e32 v23, v23, v32
	ds_write_b32 v2, v23 offset:14336
	s_waitcnt vmcnt(7)
	v_mul_f32_e32 v32, 0xbfb8aa3b, v24
	v_exp_f32_e32 v32, v32
	s_nop 0
	v_add_f32_e32 v32, 1.0, v32
	v_rcp_f32_e32 v32, v32
	s_nop 0
	v_mul_f32_e32 v24, v24, v32
	ds_write_b32 v2, v24 offset:16384
	s_waitcnt vmcnt(6)
	v_mul_f32_e32 v32, 0xbfb8aa3b, v25
	v_exp_f32_e32 v32, v32
	s_nop 0
	v_add_f32_e32 v32, 1.0, v32
	v_rcp_f32_e32 v32, v32
	s_nop 0
	v_mul_f32_e32 v25, v25, v32
	ds_write_b32 v2, v25 offset:18432
	s_waitcnt vmcnt(5)
	v_mul_f32_e32 v32, 0xbfb8aa3b, v26
	v_exp_f32_e32 v32, v32
	s_nop 0
	v_add_f32_e32 v32, 1.0, v32
	v_rcp_f32_e32 v32, v32
	s_nop 0
	v_mul_f32_e32 v26, v26, v32
	ds_write_b32 v2, v26 offset:20480
	s_waitcnt vmcnt(4)
	v_mul_f32_e32 v32, 0xbfb8aa3b, v27
	v_exp_f32_e32 v32, v32
	s_nop 0
	v_add_f32_e32 v32, 1.0, v32
	v_rcp_f32_e32 v32, v32
	s_nop 0
	v_mul_f32_e32 v27, v27, v32
	ds_write_b32 v2, v27 offset:22528
	s_waitcnt vmcnt(3)
	v_mul_f32_e32 v32, 0xbfb8aa3b, v28
	v_exp_f32_e32 v32, v32
	s_nop 0
	v_add_f32_e32 v32, 1.0, v32
	v_rcp_f32_e32 v32, v32
	s_nop 0
	v_mul_f32_e32 v28, v28, v32
	ds_write_b32 v2, v28 offset:24576
	s_waitcnt vmcnt(2)
	v_mul_f32_e32 v32, 0xbfb8aa3b, v29
	v_exp_f32_e32 v32, v32
	s_nop 0
	v_add_f32_e32 v32, 1.0, v32
	v_rcp_f32_e32 v32, v32
	s_nop 0
	v_mul_f32_e32 v29, v29, v32
	ds_write_b32 v2, v29 offset:26624
	s_waitcnt vmcnt(1)
	v_mul_f32_e32 v32, 0xbfb8aa3b, v30
	v_exp_f32_e32 v32, v32
	s_nop 0
	v_add_f32_e32 v32, 1.0, v32
	v_rcp_f32_e32 v32, v32
	s_nop 0
	v_mul_f32_e32 v30, v30, v32
	ds_write_b32 v2, v30 offset:28672
	s_waitcnt vmcnt(0)
	v_mul_f32_e32 v32, 0xbfb8aa3b, v31
	v_exp_f32_e32 v32, v32
	s_nop 0
	v_add_f32_e32 v32, 1.0, v32
	v_rcp_f32_e32 v32, v32
	s_nop 0
	v_mul_f32_e32 v31, v31, v32
	ds_write_b32 v2, v31 offset:30720
	v_add_u32_e32 v2, 0x8000, v2
	global_load_dword v16, v[0:1], off
	v_lshl_add_u64 v[0:1], v[0:1], 0, s[12:13]
	global_load_dword v17, v[0:1], off
	v_lshl_add_u64 v[0:1], v[0:1], 0, s[12:13]
	global_load_dword v18, v[0:1], off
	v_lshl_add_u64 v[0:1], v[0:1], 0, s[12:13]
	global_load_dword v19, v[0:1], off
	v_lshl_add_u64 v[0:1], v[0:1], 0, s[12:13]
	global_load_dword v20, v[0:1], off
	v_lshl_add_u64 v[0:1], v[0:1], 0, s[12:13]
	global_load_dword v21, v[0:1], off
	v_lshl_add_u64 v[0:1], v[0:1], 0, s[12:13]
	global_load_dword v22, v[0:1], off
	v_lshl_add_u64 v[0:1], v[0:1], 0, s[12:13]
	global_load_dword v23, v[0:1], off
	v_lshl_add_u64 v[0:1], v[0:1], 0, s[12:13]
	global_load_dword v24, v[0:1], off
	v_lshl_add_u64 v[0:1], v[0:1], 0, s[12:13]
	global_load_dword v25, v[0:1], off
	v_lshl_add_u64 v[0:1], v[0:1], 0, s[12:13]
	global_load_dword v26, v[0:1], off
	v_lshl_add_u64 v[0:1], v[0:1], 0, s[12:13]
	global_load_dword v27, v[0:1], off
	v_lshl_add_u64 v[0:1], v[0:1], 0, s[12:13]
	global_load_dword v28, v[0:1], off
	v_lshl_add_u64 v[0:1], v[0:1], 0, s[12:13]
	global_load_dword v29, v[0:1], off
	v_lshl_add_u64 v[0:1], v[0:1], 0, s[12:13]
	global_load_dword v30, v[0:1], off
	v_lshl_add_u64 v[0:1], v[0:1], 0, s[12:13]
	global_load_dword v31, v[0:1], off
	v_lshl_add_u64 v[0:1], v[0:1], 0, s[12:13]
	s_waitcnt vmcnt(15)
	v_mul_f32_e32 v32, 0xbfb8aa3b, v16
	v_exp_f32_e32 v32, v32
	s_nop 0
	v_add_f32_e32 v32, 1.0, v32
	v_rcp_f32_e32 v32, v32
	s_nop 0
	v_mul_f32_e32 v16, v16, v32
	ds_write_b32 v2, v16
	s_waitcnt vmcnt(14)
	v_mul_f32_e32 v32, 0xbfb8aa3b, v17
	v_exp_f32_e32 v32, v32
	s_nop 0
	v_add_f32_e32 v32, 1.0, v32
	v_rcp_f32_e32 v32, v32
	s_nop 0
	v_mul_f32_e32 v17, v17, v32
	ds_write_b32 v2, v17 offset:2048
	s_waitcnt vmcnt(13)
; __device__ __forceinline__ float siluf_(float x) { return x * sigmoidf_(x); }
; __device__ __forceinline__ void p0_phase(LAS unsigned char* lds, const float* c, const float* w_ada, const float* b_ada, const float* w_in, const float* w_out,
;                                          float* mod, bf16* win_t, bf16* wout_t, int tid, int wid, int lane) {
;     ...
;         const int l = unit / 48, nb = unit % 48;
;         __syncthreads();
;         for (int i = tid; i < 32 * 1024; i += 512) { const float cv = c[i]; cs[i] = siluf_(cv); }
;         __syncthreads();
;         const int n = nb * 64 + lane, kbase = wid * 128;
;         const float* wp = w_ada + (size_t)l * 1024 * 3072 + (size_t)kbase * 3072 + n;
;         float acc[32];
; #pragma unroll
;         for (int b = 0; b < 32; ++b) acc[b] = 0.f;
	v_mul_f32_e32 v32, 0xbfb8aa3b, v18
	v_exp_f32_e32 v32, v32
	s_nop 0
	v_add_f32_e32 v32, 1.0, v32
	v_rcp_f32_e32 v32, v32
	s_nop 0
	v_mul_f32_e32 v18, v18, v32
	ds_write_b32 v2, v18 offset:4096
	s_waitcnt vmcnt(12)
	v_mul_f32_e32 v32, 0xbfb8aa3b, v19
	v_exp_f32_e32 v32, v32
	s_nop 0
	v_add_f32_e32 v32, 1.0, v32
	v_rcp_f32_e32 v32, v32
	s_nop 0
	v_mul_f32_e32 v19, v19, v32
	ds_write_b32 v2, v19 offset:6144
	s_waitcnt vmcnt(11)
	v_mul_f32_e32 v32, 0xbfb8aa3b, v20
	v_exp_f32_e32 v32, v32
	s_nop 0
	v_add_f32_e32 v32, 1.0, v32
	v_rcp_f32_e32 v32, v32
	s_nop 0
	v_mul_f32_e32 v20, v20, v32
	ds_write_b32 v2, v20 offset:8192
	s_waitcnt vmcnt(10)
	v_mul_f32_e32 v32, 0xbfb8aa3b, v21
	v_exp_f32_e32 v32, v32
	s_nop 0
	v_add_f32_e32 v32, 1.0, v32
	v_rcp_f32_e32 v32, v32
	s_nop 0
	v_mul_f32_e32 v21, v21, v32
	ds_write_b32 v2, v21 offset:10240
	s_waitcnt vmcnt(9)
	v_mul_f32_e32 v32, 0xbfb8aa3b, v22
	v_exp_f32_e32 v32, v32
	s_nop 0
	v_add_f32_e32 v32, 1.0, v32
	v_rcp_f32_e32 v32, v32
	s_nop 0
	v_mul_f32_e32 v22, v22, v32
	ds_write_b32 v2, v22 offset:12288
	s_waitcnt vmcnt(8)
	v_mul_f32_e32 v32, 0xbfb8aa3b, v23
	v_exp_f32_e32 v32, v32
	s_nop 0
	v_add_f32_e32 v32, 1.0, v32
	v_rcp_f32_e32 v32, v32
	s_nop 0
	v_mul_f32_e32 v23, v23, v32
	ds_write_b32 v2, v23 offset:14336
	s_waitcnt vmcnt(7)
	v_mul_f32_e32 v32, 0xbfb8aa3b, v24
	v_exp_f32_e32 v32, v32
	s_nop 0
	v_add_f32_e32 v32, 1.0, v32
	v_rcp_f32_e32 v32, v32
	s_nop 0
	v_mul_f32_e32 v24, v24, v32
	ds_write_b32 v2, v24 offset:16384
	s_waitcnt vmcnt(6)
	v_mul_f32_e32 v32, 0xbfb8aa3b, v25
	v_exp_f32_e32 v32, v32
	s_nop 0
	v_add_f32_e32 v32, 1.0, v32
	v_rcp_f32_e32 v32, v32
	s_nop 0
	v_mul_f32_e32 v25, v25, v32
	ds_write_b32 v2, v25 offset:18432
	s_waitcnt vmcnt(5)
	v_mul_f32_e32 v32, 0xbfb8aa3b, v26
	v_exp_f32_e32 v32, v32
	s_nop 0
	v_add_f32_e32 v32, 1.0, v32
	v_rcp_f32_e32 v32, v32
	s_nop 0
	v_mul_f32_e32 v26, v26, v32
	ds_write_b32 v2, v26 offset:20480
	s_waitcnt vmcnt(4)
	v_mul_f32_e32 v32, 0xbfb8aa3b, v27
	v_exp_f32_e32 v32, v32
	s_nop 0
	v_add_f32_e32 v32, 1.0, v32
	v_rcp_f32_e32 v32, v32
	s_nop 0
	v_mul_f32_e32 v27, v27, v32
	ds_write_b32 v2, v27 offset:22528
	s_waitcnt vmcnt(3)
	v_mul_f32_e32 v32, 0xbfb8aa3b, v28
	v_exp_f32_e32 v32, v32
	s_nop 0
	v_add_f32_e32 v32, 1.0, v32
	v_rcp_f32_e32 v32, v32
	s_nop 0
	v_mul_f32_e32 v28, v28, v32
	ds_write_b32 v2, v28 offset:24576
	s_waitcnt vmcnt(2)
	v_mul_f32_e32 v32, 0xbfb8aa3b, v29
	v_exp_f32_e32 v32, v32
	s_nop 0
	v_add_f32_e32 v32, 1.0, v32
	v_rcp_f32_e32 v32, v32
	s_nop 0
	v_mul_f32_e32 v29, v29, v32
	ds_write_b32 v2, v29 offset:26624
	s_waitcnt vmcnt(1)
	v_mul_f32_e32 v32, 0xbfb8aa3b, v30
	v_exp_f32_e32 v32, v32
	s_nop 0
	v_add_f32_e32 v32, 1.0, v32
	v_rcp_f32_e32 v32, v32
	s_nop 0
	v_mul_f32_e32 v30, v30, v32
	ds_write_b32 v2, v30 offset:28672
	s_waitcnt vmcnt(0)
	v_mul_f32_e32 v32, 0xbfb8aa3b, v31
	v_exp_f32_e32 v32, v32
	s_nop 0
	v_add_f32_e32 v32, 1.0, v32
	v_rcp_f32_e32 v32, v32
	s_nop 0
	v_mul_f32_e32 v31, v31, v32
	ds_write_b32 v2, v31 offset:30720
	v_add_u32_e32 v2, 0x8000, v2
	s_or_b64 exec, exec, s[16:17]
	s_mul_hi_i32 s16, s31, 0x2aaaaaab
	s_lshr_b32 s17, s16, 31
	s_ashr_i32 s16, s16, 3
	s_add_i32 s16, s16, s17
	s_ashr_i32 s17, s16, 31
	s_mul_i32 s34, s16, 0xc00000
	v_lshl_or_b32 v0, s31, 6, v203
	s_mul_i32 s33, s16, 0xc00
	s_mul_hi_i32 s35, s16, 0xc00000
	v_subrev_u32_e32 v0, s33, v0
	s_add_u32 s34, s21, s34
	v_ashrrev_i32_e32 v1, 31, v0
	s_addc_u32 s35, s22, s35
	v_mov_b32_e32 v34, 0
	v_lshl_add_u64 v[16:17], v[0:1], 2, s[34:35]
	s_mov_b32 s34, -4
	s_mov_b32 s35, s18
	v_mov_b32_e32 v35, v34
	v_mov_b32_e32 v18, v34
	v_mov_b32_e32 v19, v34
	v_mov_b32_e32 v20, v34
	v_mov_b32_e32 v21, v34
	v_mov_b32_e32 v22, v34
	v_mov_b32_e32 v23, v34
	v_mov_b32_e32 v24, v34
	v_mov_b32_e32 v25, v34
	v_mov_b32_e32 v26, v34
	v_mov_b32_e32 v27, v34
	v_mov_b32_e32 v28, v34
	v_mov_b32_e32 v29, v34
	v_mov_b32_e32 v30, v34
	v_mov_b32_e32 v31, v34
	v_mov_b32_e32 v32, v34
	v_mov_b32_e32 v33, v34
	v_mov_b32_e32 v52, v34
	v_mov_b32_e32 v53, v34
	v_mov_b32_e32 v54, v34
	v_mov_b32_e32 v55, v34
	v_mov_b32_e32 v56, v34
	v_mov_b32_e32 v57, v34
	v_mov_b32_e32 v50, v34
	v_mov_b32_e32 v51, v34
	v_mov_b32_e32 v48, v34
	v_mov_b32_e32 v49, v34
	v_mov_b32_e32 v46, v34
	v_mov_b32_e32 v47, v34
	v_mov_b32_e32 v44, v34
	v_mov_b32_e32 v45, v34
	s_waitcnt lgkmcnt(0)
	s_barrier

;     __device__ __forceinline__ void operator()(const f32x4 (&acc)[2][2][4][2], const pg8::Unit& u, int wr, int wc, int fr, int fq) const {
;         const int row0 = u.pm * 256 + wr * 64 + fr, col0 = u.pn * 256 + wc * 32 + 4 * fq;
;         const float* gp = gatev + (size_t)(u.pm >> 3) * 3072 + col0;
;         f32x4 gv[2][2];
; #pragma unroll
;         for (int bj = 0; bj < 2; ++bj)
; #pragma unroll
;             for (int n = 0; n < 2; ++n) gv[bj][n] = *(const f32x4*)(gp + bj * 128 + n * 16);
; #pragma unroll
;         for (int ai = 0; ai < 2; ++ai)
; #pragma unroll
;             for (int m = 0; m < 4; ++m) {
;                 const size_t off = (size_t)(row0 + ai * 128 + m * 16) * DM + col0;
; #pragma unroll
;                 for (int bj = 0; bj < 2; ++bj)
; #pragma unroll
;                     for (int n = 0; n < 2; ++n) {
;                         const f32x4 xv = *(const f32x4*)(xin + off + bj * 128 + n * 16);
;                         *(f32x4*)(out + off + bj * 128 + n * 16) = xv + gv[bj][n] * acc[ai][bj][m][n];
;                     }
;                 if (m == 3) asm volatile("" ::: "memory");
;             }
.LBB0_582:
	v_lshl_add_u32 v170, s30, 8, v158
	v_lshl_or_b32 v168, s56, 8, v160
	s_ashr_i32 s23, s30, 3
	v_ashrrev_i32_e32 v171, 31, v170
	s_mul_hi_i32 s25, s23, 0x3000
	s_mulk_i32 s23, 0x3000
	v_ashrrev_i32_e32 v169, 31, v168
	v_lshlrev_b64 v[130:131], 10, v[170:171]
	s_add_u32 s34, s49, s23
	v_lshl_add_u64 v[130:131], v[130:131], 0, v[168:169]
	s_addc_u32 s35, s50, s25
	v_lshlrev_b64 v[156:157], 2, v[130:131]
	v_lshl_add_u64 v[128:129], v[168:169], 2, s[34:35]
	global_load_dwordx4 v[140:143], v[128:129], off
	global_load_dwordx4 v[136:139], v[128:129], off offset:64
	global_load_dwordx4 v[132:135], v[128:129], off offset:512
	s_nop 0
	global_load_dwordx4 v[128:131], v[128:129], off offset:576
	s_andn2_b64 vcc, exec, s[4:5]
	s_mov_b64 s[4:5], -1
	s_mov_b64 s[98:99], s[0:1]
	global_load_dwordx4 v[164:167], v156, s[98:99]
	global_load_dwordx4 v[168:171], v156, s[98:99] offset:64
	global_load_dwordx4 v[172:175], v156, s[98:99] offset:512
	global_load_dwordx4 v[176:179], v156, s[98:99] offset:576
	s_add_u32 s98, s0, 0x10000
	s_addc_u32 s99, s1, 0
	global_load_dwordx4 v[180:183], v156, s[98:99]
	global_load_dwordx4 v[184:187], v156, s[98:99] offset:64
	global_load_dwordx4 v[188:191], v156, s[98:99] offset:512
	global_load_dwordx4 v[192:195], v156, s[98:99] offset:576
	s_add_u32 s98, s0, 0x20000
	s_addc_u32 s99, s1, 0
	global_load_dwordx4 v[196:199], v156, s[98:99]
	global_load_dwordx4 v[204:207], v156, s[98:99] offset:64
	global_load_dwordx4 v[208:211], v156, s[98:99] offset:512
	global_load_dwordx4 v[212:215], v156, s[98:99] offset:576
	s_waitcnt vmcnt(8)
	v_pk_fma_f32 v[166:167], v[126:127], v[142:143], v[166:167]
	v_pk_fma_f32 v[164:165], v[124:125], v[140:141], v[164:165]
	v_pk_fma_f32 v[170:171], v[122:123], v[138:139], v[170:171]
	v_pk_fma_f32 v[168:169], v[120:121], v[136:137], v[168:169]
	v_pk_fma_f32 v[174:175], v[118:119], v[134:135], v[174:175]
	v_pk_fma_f32 v[172:173], v[116:117], v[132:133], v[172:173]
	v_pk_fma_f32 v[178:179], v[106:107], v[130:131], v[178:179]
	v_pk_fma_f32 v[176:177], v[104:105], v[128:129], v[176:177]
	s_mov_b64 s[100:101], s[8:9]
	global_store_dwordx4 v156, v[164:167], s[100:101]
	global_store_dwordx4 v156, v[168:171], s[100:101] offset:64
	global_store_dwordx4 v156, v[172:175], s[100:101] offset:512
	global_store_dwordx4 v156, v[176:179], s[100:101] offset:576
	s_add_u32 s98, s0, 0x30000
	s_addc_u32 s99, s1, 0
	global_load_dwordx4 v[164:167], v156, s[98:99]
	global_load_dwordx4 v[168:171], v156, s[98:99] offset:64
	global_load_dwordx4 v[172:175], v156, s[98:99] offset:512
	global_load_dwordx4 v[176:179], v156, s[98:99] offset:576
	s_waitcnt vmcnt(12)
	v_pk_fma_f32 v[182:183], v[114:115], v[142:143], v[182:183]
	v_pk_fma_f32 v[180:181], v[112:113], v[140:141], v[180:181]
	v_pk_fma_f32 v[186:187], v[110:111], v[138:139], v[186:187]
	v_pk_fma_f32 v[184:185], v[108:109], v[136:137], v[184:185]
	v_pk_fma_f32 v[190:191], v[102:103], v[134:135], v[190:191]
	v_pk_fma_f32 v[188:189], v[100:101], v[132:133], v[188:189]
	v_pk_fma_f32 v[194:195], v[90:91], v[130:131], v[194:195]
	v_pk_fma_f32 v[192:193], v[88:89], v[128:129], v[192:193]
	s_add_u32 s100, s8, 0x10000
	s_addc_u32 s101, s9, 0
	global_store_dwordx4 v156, v[180:183], s[100:101]
	global_store_dwordx4 v156, v[184:187], s[100:101] offset:64
	global_store_dwordx4 v156, v[188:191], s[100:101] offset:512
	global_store_dwordx4 v156, v[192:195], s[100:101] offset:576
	s_add_u32 s98, s0, 0x80000
	s_addc_u32 s99, s1, 0
	global_load_dwordx4 v[180:183], v156, s[98:99]
	global_load_dwordx4 v[184:187], v156, s[98:99] offset:64
	global_load_dwordx4 v[188:191], v156, s[98:99] offset:512
	global_load_dwordx4 v[192:195], v156, s[98:99] offset:576
	s_waitcnt vmcnt(16)
	v_pk_fma_f32 v[198:199], v[98:99], v[142:143], v[198:199]
	v_pk_fma_f32 v[196:197], v[96:97], v[140:141], v[196:197]
	v_pk_fma_f32 v[206:207], v[94:95], v[138:139], v[206:207]
	v_pk_fma_f32 v[204:205], v[92:93], v[136:137], v[204:205]
	v_pk_fma_f32 v[210:211], v[86:87], v[134:135], v[210:211]
	v_pk_fma_f32 v[208:209], v[84:85], v[132:133], v[208:209]
	v_pk_fma_f32 v[214:215], v[74:75], v[130:131], v[214:215]
	v_pk_fma_f32 v[212:213], v[72:73], v[128:129], v[212:213]
	s_add_u32 s100, s8, 0x20000
	s_addc_u32 s101, s9, 0
	global_store_dwordx4 v156, v[196:199], s[100:101]
	global_store_dwordx4 v156, v[204:207], s[100:101] offset:64
	global_store_dwordx4 v156, v[208:211], s[100:101] offset:512
	global_store_dwordx4 v156, v[212:215], s[100:101] offset:576
	s_add_u32 s98, s0, 0x90000
	s_addc_u32 s99, s1, 0
	global_load_dwordx4 v[196:199], v156, s[98:99]
	global_load_dwordx4 v[204:207], v156, s[98:99] offset:64
	global_load_dwordx4 v[208:211], v156, s[98:99] offset:512
	global_load_dwordx4 v[212:215], v156, s[98:99] offset:576
	s_waitcnt vmcnt(16)
;     __device__ __forceinline__ void operator()(const f32x4 (&acc)[2][2][4][2], const pg8::Unit& u, int wr, int wc, int fr, int fq) const {
;     ...
;         for (int ai = 0; ai < 2; ++ai)
; #pragma unroll
;             for (int m = 0; m < 4; ++m) {
;                 const size_t off = (size_t)(row0 + ai * 128 + m * 16) * DM + col0;
; #pragma unroll
;                 for (int bj = 0; bj < 2; ++bj)
; #pragma unroll
;                     for (int n = 0; n < 2; ++n) {
;                         const f32x4 xv = *(const f32x4*)(xin + off + bj * 128 + n * 16);
;                         *(f32x4*)(out + off + bj * 128 + n * 16) = xv + gv[bj][n] * acc[ai][bj][m][n];
;                     }
;                 if (m == 3) asm volatile("" ::: "memory");
;             }
	v_pk_fma_f32 v[166:167], v[82:83], v[142:143], v[166:167]
	v_pk_fma_f32 v[164:165], v[80:81], v[140:141], v[164:165]
	v_pk_fma_f32 v[170:171], v[78:79], v[138:139], v[170:171]
	v_pk_fma_f32 v[168:169], v[76:77], v[136:137], v[168:169]
	v_pk_fma_f32 v[174:175], v[70:71], v[134:135], v[174:175]
	v_pk_fma_f32 v[172:173], v[68:69], v[132:133], v[172:173]
	v_pk_fma_f32 v[178:179], v[66:67], v[130:131], v[178:179]
	v_pk_fma_f32 v[176:177], v[64:65], v[128:129], v[176:177]
	s_add_u32 s100, s8, 0x30000
	s_addc_u32 s101, s9, 0
	global_store_dwordx4 v156, v[164:167], s[100:101]
	global_store_dwordx4 v156, v[168:171], s[100:101] offset:64
	global_store_dwordx4 v156, v[172:175], s[100:101] offset:512
	global_store_dwordx4 v156, v[176:179], s[100:101] offset:576
	s_add_u32 s98, s0, 0xa0000
	s_addc_u32 s99, s1, 0
	global_load_dwordx4 v[164:167], v156, s[98:99]
	global_load_dwordx4 v[168:171], v156, s[98:99] offset:64
	global_load_dwordx4 v[172:175], v156, s[98:99] offset:512
	global_load_dwordx4 v[176:179], v156, s[98:99] offset:576
	s_waitcnt vmcnt(16)
	v_pk_fma_f32 v[182:183], v[62:63], v[142:143], v[182:183]
	v_pk_fma_f32 v[180:181], v[60:61], v[140:141], v[180:181]
	v_pk_fma_f32 v[186:187], v[58:59], v[138:139], v[186:187]
	v_pk_fma_f32 v[184:185], v[56:57], v[136:137], v[184:185]
	v_pk_fma_f32 v[190:191], v[54:55], v[134:135], v[190:191]
	v_pk_fma_f32 v[188:189], v[52:53], v[132:133], v[188:189]
	v_pk_fma_f32 v[194:195], v[42:43], v[130:131], v[194:195]
	v_pk_fma_f32 v[192:193], v[40:41], v[128:129], v[192:193]
	s_add_u32 s100, s8, 0x80000
	s_addc_u32 s101, s9, 0
	global_store_dwordx4 v156, v[180:183], s[100:101]
	global_store_dwordx4 v156, v[184:187], s[100:101] offset:64
	global_store_dwordx4 v156, v[188:191], s[100:101] offset:512
	global_store_dwordx4 v156, v[192:195], s[100:101] offset:576
	s_add_u32 s98, s0, 0xb0000
	s_addc_u32 s99, s1, 0
	global_load_dwordx4 v[180:183], v156, s[98:99]
	global_load_dwordx4 v[184:187], v156, s[98:99] offset:64
	global_load_dwordx4 v[188:191], v156, s[98:99] offset:512
	global_load_dwordx4 v[192:195], v156, s[98:99] offset:576
	s_waitcnt vmcnt(16)
	v_pk_fma_f32 v[198:199], v[50:51], v[142:143], v[198:199]
	v_pk_fma_f32 v[196:197], v[48:49], v[140:141], v[196:197]
	v_pk_fma_f32 v[206:207], v[46:47], v[138:139], v[206:207]
	v_pk_fma_f32 v[204:205], v[44:45], v[136:137], v[204:205]
	v_pk_fma_f32 v[210:211], v[38:39], v[134:135], v[210:211]
	v_pk_fma_f32 v[208:209], v[36:37], v[132:133], v[208:209]
	v_pk_fma_f32 v[214:215], v[26:27], v[130:131], v[214:215]
	v_pk_fma_f32 v[212:213], v[24:25], v[128:129], v[212:213]
	s_add_u32 s100, s8, 0x90000
	s_addc_u32 s101, s9, 0
	global_store_dwordx4 v156, v[196:199], s[100:101]
	global_store_dwordx4 v156, v[204:207], s[100:101] offset:64
	global_store_dwordx4 v156, v[208:211], s[100:101] offset:512
	global_store_dwordx4 v156, v[212:215], s[100:101] offset:576
	s_waitcnt vmcnt(12)
	v_pk_fma_f32 v[166:167], v[34:35], v[142:143], v[166:167]
	v_pk_fma_f32 v[164:165], v[32:33], v[140:141], v[164:165]
	v_pk_fma_f32 v[170:171], v[30:31], v[138:139], v[170:171]
	v_pk_fma_f32 v[168:169], v[28:29], v[136:137], v[168:169]
	v_pk_fma_f32 v[174:175], v[22:23], v[134:135], v[174:175]
	v_pk_fma_f32 v[172:173], v[20:21], v[132:133], v[172:173]
	v_pk_fma_f32 v[178:179], v[10:11], v[130:131], v[178:179]
	v_pk_fma_f32 v[176:177], v[8:9], v[128:129], v[176:177]
	s_add_u32 s100, s8, 0xa0000
	s_addc_u32 s101, s9, 0
	global_store_dwordx4 v156, v[164:167], s[100:101]
	global_store_dwordx4 v156, v[168:171], s[100:101] offset:64
	global_store_dwordx4 v156, v[172:175], s[100:101] offset:512
	global_store_dwordx4 v156, v[176:179], s[100:101] offset:576
	s_waitcnt vmcnt(8)
	v_pk_fma_f32 v[182:183], v[18:19], v[142:143], v[182:183]
	v_pk_fma_f32 v[180:181], v[16:17], v[140:141], v[180:181]
	v_pk_fma_f32 v[186:187], v[14:15], v[138:139], v[186:187]
	v_pk_fma_f32 v[184:185], v[12:13], v[136:137], v[184:185]
	v_pk_fma_f32 v[190:191], v[6:7], v[134:135], v[190:191]
	v_pk_fma_f32 v[188:189], v[4:5], v[132:133], v[188:189]
	v_pk_fma_f32 v[194:195], v[2:3], v[130:131], v[194:195]
	v_pk_fma_f32 v[192:193], v[0:1], v[128:129], v[192:193]
	s_add_u32 s100, s8, 0xb0000
	s_addc_u32 s101, s9, 0
	global_store_dwordx4 v156, v[180:183], s[100:101]
	global_store_dwordx4 v156, v[184:187], s[100:101] offset:64
	global_store_dwordx4 v156, v[188:191], s[100:101] offset:512
	global_store_dwordx4 v156, v[192:195], s[100:101] offset:576
	s_cbranch_vccnz .LBB0_571
	s_andn2_b64 vcc, exec, s[6:7]
	s_cbranch_vccnz .LBB0_570
	s_barrier
	s_branch .LBB0_570

; #define LAS __attribute__((address_space(3)))
; __global__ void __launch_bounds__(512, 2) hybrid_fwd(Args a) {
;     extern __shared__ __attribute__((aligned(16))) unsigned char lds_raw[];
;     LAS unsigned char* lds = (LAS unsigned char*)lds_raw;
;     const int tid = threadIdx.x, lane = tid & 63, wid = __builtin_amdgcn_readfirstlane(tid >> 6);
	.amdhsa_kernel _Z10hybrid_fwd4Args
		.amdhsa_group_segment_fixed_size 0
		.amdhsa_private_segment_fixed_size 0
		.amdhsa_kernarg_size 416
		.amdhsa_user_sgpr_count 2
		.amdhsa_user_sgpr_dispatch_ptr 0
		.amdhsa_user_sgpr_queue_ptr 0
		.amdhsa_user_sgpr_kernarg_segment_ptr 1
		.amdhsa_user_sgpr_dispatch_id 0
		.amdhsa_user_sgpr_kernarg_preload_length 0
		.amdhsa_user_sgpr_kernarg_preload_offset 0
		.amdhsa_user_sgpr_private_segment_size 0
		.amdhsa_uses_dynamic_stack 0
		.amdhsa_enable_private_segment 0
		.amdhsa_system_sgpr_workgroup_id_x 1
		.amdhsa_system_sgpr_workgroup_id_y 0
		.amdhsa_system_sgpr_workgroup_id_z 0
		.amdhsa_system_sgpr_workgroup_info 0
		.amdhsa_system_vgpr_workitem_id 2
		.amdhsa_next_free_vgpr 250
		.amdhsa_next_free_sgpr 102
		.amdhsa_accum_offset 252
		.amdhsa_reserve_vcc 1
		.amdhsa_float_round_mode_32 0
		.amdhsa_float_round_mode_16_64 0
		.amdhsa_float_denorm_mode_32 3
		.amdhsa_float_denorm_mode_16_64 3
		.amdhsa_dx10_clamp 1
		.amdhsa_ieee_mode 1
		.amdhsa_fp16_overflow 0
		.amdhsa_tg_split 0
		.amdhsa_exception_fp_ieee_invalid_op 0
		.amdhsa_exception_fp_denorm_src 0
		.amdhsa_exception_fp_ieee_div_zero 0
		.amdhsa_exception_fp_ieee_overflow 0
		.amdhsa_exception_fp_ieee_underflow 0
		.amdhsa_exception_fp_ieee_inexact 0
		.amdhsa_exception_int_div_zero 0
	.end_amdhsa_kernel

; #define LAS __attribute__((address_space(3)))
; __global__ void __launch_bounds__(512, 2) hybrid_fwd(Args a) {
;     extern __shared__ __attribute__((aligned(16))) unsigned char lds_raw[];
;     LAS unsigned char* lds = (LAS unsigned char*)lds_raw;
;     const int tid = threadIdx.x, lane = tid & 63, wid = __builtin_amdgcn_readfirstlane(tid >> 6);
amdhsa.kernels:
  - .agpr_count:     0
    .args:
      - .offset:         0
        .size:           160
        .value_kind:     by_value
      - .offset:         160
        .size:           4
        .value_kind:     hidden_block_count_x
      - .offset:         164
        .size:           4
        .value_kind:     hidden_block_count_y
      - .offset:         168
        .size:           4
        .value_kind:     hidden_block_count_z
      - .offset:         172
        .size:           2
        .value_kind:     hidden_group_size_x
      - .offset:         174
        .size:           2
        .value_kind:     hidden_group_size_y
      - .offset:         176
        .size:           2
        .value_kind:     hidden_group_size_z
      - .offset:         178
        .size:           2
        .value_kind:     hidden_remainder_x
      - .offset:         180
        .size:           2
        .value_kind:     hidden_remainder_y
      - .offset:         182
        .size:           2
        .value_kind:     hidden_remainder_z
      - .offset:         200
        .size:           8
        .value_kind:     hidden_global_offset_x
      - .offset:         208
        .size:           8
        .value_kind:     hidden_global_offset_y
      - .offset:         216
        .size:           8
        .value_kind:     hidden_global_offset_z
      - .offset:         224
        .size:           2
        .value_kind:     hidden_grid_dims
      - .offset:         248
        .size:           8
        .value_kind:     hidden_multigrid_sync_arg
      - .offset:         280
        .size:           4
        .value_kind:     hidden_dynamic_lds_size
    .group_segment_fixed_size: 0
    .kernarg_segment_align: 8
    .kernarg_segment_size: 416
    .language:       OpenCL C
    .language_version:
      - 2
      - 0
    .max_flat_workgroup_size: 512
    .name:           _Z10hybrid_fwd4Args
    .private_segment_fixed_size: 0
    .sgpr_count:     108
    .sgpr_spill_count: 158
    .symbol:         _Z10hybrid_fwd4Args.kd
    .uniform_work_group_size: 1
    .uses_dynamic_stack: false
    .vgpr_count:     250
    .vgpr_spill_count: 0
    .wavefront_size: 64
